# GEMM K-loops: the two K-half MFMAs of each accumulator issued back to back (accumulate chain / SrcC forwarding) instead of 8 apart; plus barrier and wait edits of previous version
# speedup vs baseline: 1.0182x; 1.0081x over previous
.LBB0_131:
	ds_read_b128 v[146:149], v157
	ds_read_b128 v[150:153], v157 offset:1024
	ds_read_b128 v[160:163], v157 offset:2048
	ds_read_b128 v[164:167], v157 offset:3072
	ds_read_b128 v[168:171], v158
	ds_read_b128 v[172:175], v158 offset:1024
	ds_read_b128 v[176:179], v158 offset:2048
	ds_read_b128 v[180:183], v158 offset:3072
	s_add_u32 s34, s30, 0xfff80080
	s_addc_u32 s35, s31, -1
	s_cmp_eq_u32 s55, 28
	s_cselect_b32 s37, s23, s35
	s_cselect_b32 s36, s51, s34
	s_cselect_b32 s35, s21, s54
	s_cselect_b32 s34, s52, s53
	v_lshl_add_u64 v[216:217], s[30:31], 0, v[138:139]
	s_add_i32 m0, s29, 0xc000
	ds_read_b128 v[184:187], v159
	ds_read_b128 v[188:191], v159 offset:1024
	ds_read_b128 v[192:195], v159 offset:2048
	ds_read_b128 v[196:199], v159 offset:3072
	ds_read_b128 v[200:203], v159 offset:4096
	ds_read_b128 v[204:207], v159 offset:5120
	ds_read_b128 v[208:211], v159 offset:6144
	ds_read_b128 v[212:215], v159 offset:7168
	global_load_lds_dwordx4 v[216:217], off
	v_lshl_add_u64 v[216:217], s[30:31], 0, v[140:141]
	s_add_i32 m0, s29, 0xe000
	s_nop 0
	global_load_lds_dwordx4 v[216:217], off
	s_waitcnt vmcnt(8)
	s_waitcnt lgkmcnt(0)
	s_barrier
	s_setprio 1
	s_waitcnt lgkmcnt(0)
	v_mfma_f32_16x16x32_bf16 v[124:127], v[146:149], v[184:187], v[124:127]
	v_mfma_f32_16x16x32_bf16 v[124:127], v[150:153], v[188:191], v[124:127]
	v_mfma_f32_16x16x32_bf16 v[120:123], v[160:163], v[184:187], v[120:123]
	v_mfma_f32_16x16x32_bf16 v[120:123], v[164:167], v[188:191], v[120:123]
	v_mfma_f32_16x16x32_bf16 v[108:111], v[146:149], v[192:195], v[108:111]
	v_mfma_f32_16x16x32_bf16 v[108:111], v[150:153], v[196:199], v[108:111]
	v_mfma_f32_16x16x32_bf16 v[104:107], v[160:163], v[192:195], v[104:107]
	v_mfma_f32_16x16x32_bf16 v[104:107], v[164:167], v[196:199], v[104:107]
	v_mfma_f32_16x16x32_bf16 v[92:95], v[146:149], v[200:203], v[92:95]
	v_mfma_f32_16x16x32_bf16 v[92:95], v[150:153], v[204:207], v[92:95]
	v_mfma_f32_16x16x32_bf16 v[88:91], v[160:163], v[200:203], v[88:91]
	v_mfma_f32_16x16x32_bf16 v[88:91], v[164:167], v[204:207], v[88:91]
	v_mfma_f32_16x16x32_bf16 v[76:79], v[146:149], v[208:211], v[76:79]
	v_mfma_f32_16x16x32_bf16 v[76:79], v[150:153], v[212:215], v[76:79]
	v_mfma_f32_16x16x32_bf16 v[72:75], v[160:163], v[208:211], v[72:75]
	v_mfma_f32_16x16x32_bf16 v[72:75], v[164:167], v[212:215], v[72:75]
	s_setprio 0
	s_setprio 1
	v_mfma_f32_16x16x32_bf16 v[116:119], v[168:171], v[184:187], v[116:119]
	v_mfma_f32_16x16x32_bf16 v[116:119], v[172:175], v[188:191], v[116:119]
	v_mfma_f32_16x16x32_bf16 v[112:115], v[176:179], v[184:187], v[112:115]
	v_mfma_f32_16x16x32_bf16 v[112:115], v[180:183], v[188:191], v[112:115]
	v_mfma_f32_16x16x32_bf16 v[100:103], v[168:171], v[192:195], v[100:103]
	v_mfma_f32_16x16x32_bf16 v[100:103], v[172:175], v[196:199], v[100:103]
	v_mfma_f32_16x16x32_bf16 v[96:99], v[176:179], v[192:195], v[96:99]
	v_mfma_f32_16x16x32_bf16 v[96:99], v[180:183], v[196:199], v[96:99]
	v_mfma_f32_16x16x32_bf16 v[84:87], v[168:171], v[200:203], v[84:87]
	v_mfma_f32_16x16x32_bf16 v[84:87], v[172:175], v[204:207], v[84:87]
	v_mfma_f32_16x16x32_bf16 v[80:83], v[176:179], v[200:203], v[80:83]
	v_mfma_f32_16x16x32_bf16 v[80:83], v[180:183], v[204:207], v[80:83]
	v_mfma_f32_16x16x32_bf16 v[68:71], v[168:171], v[208:211], v[68:71]
	v_mfma_f32_16x16x32_bf16 v[68:71], v[172:175], v[212:215], v[68:71]
	v_mfma_f32_16x16x32_bf16 v[64:67], v[176:179], v[208:211], v[64:67]
	v_mfma_f32_16x16x32_bf16 v[64:67], v[180:183], v[212:215], v[64:67]
	s_setprio 0
	s_barrier
	s_add_i32 s56, s47, s33
	v_lshl_add_u64 v[216:217], s[34:35], 0, v[134:135]
	s_mov_b32 m0, s56
	ds_read_b128 v[184:187], v159 offset:16384
	ds_read_b128 v[188:191], v159 offset:17408
	ds_read_b128 v[192:195], v159 offset:18432
	ds_read_b128 v[196:199], v159 offset:19456
	ds_read_b128 v[200:203], v159 offset:20480
	ds_read_b128 v[204:207], v159 offset:21504
	ds_read_b128 v[208:211], v159 offset:22528
	ds_read_b128 v[212:215], v159 offset:23552
	global_load_lds_dwordx4 v[216:217], off
	s_add_i32 m0, s56, 0x2000
	s_add_u32 s56, s34, 0x80000
	v_lshl_add_u64 v[218:219], s[34:35], 0, v[130:131]
	s_addc_u32 s57, s35, 0
	s_add_i32 s58, s48, s33
	global_load_lds_dwordx4 v[218:219], off
	v_lshl_add_u64 v[220:221], s[56:57], 0, v[134:135]
	s_mov_b32 m0, s58
	v_lshl_add_u64 v[222:223], s[36:37], 0, v[132:133]
	global_load_lds_dwordx4 v[220:221], off
	v_lshl_add_u64 v[220:221], s[56:57], 0, v[130:131]
	s_add_i32 m0, s58, 0x2000
	s_nop 0
	global_load_lds_dwordx4 v[220:221], off
	v_lshl_add_u64 v[220:221], s[36:37], 0, v[136:137]
	s_mov_b32 m0, s29
	s_nop 0
	global_load_lds_dwordx4 v[220:221], off
	s_mov_b32 m0, s40
	s_nop 0
	global_load_lds_dwordx4 v[222:223], off
	s_waitcnt vmcnt(8)
	s_waitcnt lgkmcnt(0)
	s_barrier
	s_setprio 1
	s_waitcnt lgkmcnt(0)
	v_mfma_f32_16x16x32_bf16 v[60:63], v[146:149], v[184:187], v[60:63]
	v_mfma_f32_16x16x32_bf16 v[60:63], v[150:153], v[188:191], v[60:63]
	v_mfma_f32_16x16x32_bf16 v[56:59], v[160:163], v[184:187], v[56:59]
	v_mfma_f32_16x16x32_bf16 v[56:59], v[164:167], v[188:191], v[56:59]
	v_mfma_f32_16x16x32_bf16 v[44:47], v[146:149], v[192:195], v[44:47]
	v_mfma_f32_16x16x32_bf16 v[44:47], v[150:153], v[196:199], v[44:47]
	v_mfma_f32_16x16x32_bf16 v[40:43], v[160:163], v[192:195], v[40:43]
	v_mfma_f32_16x16x32_bf16 v[40:43], v[164:167], v[196:199], v[40:43]
	v_mfma_f32_16x16x32_bf16 v[28:31], v[146:149], v[200:203], v[28:31]
	v_mfma_f32_16x16x32_bf16 v[28:31], v[150:153], v[204:207], v[28:31]
	v_mfma_f32_16x16x32_bf16 v[24:27], v[160:163], v[200:203], v[24:27]
	v_mfma_f32_16x16x32_bf16 v[24:27], v[164:167], v[204:207], v[24:27]
	v_mfma_f32_16x16x32_bf16 v[12:15], v[146:149], v[208:211], v[12:15]
	v_mfma_f32_16x16x32_bf16 v[12:15], v[150:153], v[212:215], v[12:15]
	v_mfma_f32_16x16x32_bf16 v[8:11], v[160:163], v[208:211], v[8:11]
	v_mfma_f32_16x16x32_bf16 v[8:11], v[164:167], v[212:215], v[8:11]
	s_setprio 0
	s_setprio 1
	v_mfma_f32_16x16x32_bf16 v[52:55], v[168:171], v[184:187], v[52:55]
	v_mfma_f32_16x16x32_bf16 v[52:55], v[172:175], v[188:191], v[52:55]
	v_mfma_f32_16x16x32_bf16 v[48:51], v[176:179], v[184:187], v[48:51]
	v_mfma_f32_16x16x32_bf16 v[48:51], v[180:183], v[188:191], v[48:51]
	v_mfma_f32_16x16x32_bf16 v[36:39], v[168:171], v[192:195], v[36:39]
	v_mfma_f32_16x16x32_bf16 v[36:39], v[172:175], v[196:199], v[36:39]
	v_mfma_f32_16x16x32_bf16 v[32:35], v[176:179], v[192:195], v[32:35]
	v_mfma_f32_16x16x32_bf16 v[32:35], v[180:183], v[196:199], v[32:35]
	v_mfma_f32_16x16x32_bf16 v[20:23], v[168:171], v[200:203], v[20:23]
	v_mfma_f32_16x16x32_bf16 v[20:23], v[172:175], v[204:207], v[20:23]
	v_mfma_f32_16x16x32_bf16 v[16:19], v[176:179], v[200:203], v[16:19]
	v_mfma_f32_16x16x32_bf16 v[16:19], v[180:183], v[204:207], v[16:19]
	v_mfma_f32_16x16x32_bf16 v[4:7], v[168:171], v[208:211], v[4:7]
	v_mfma_f32_16x16x32_bf16 v[4:7], v[172:175], v[212:215], v[4:7]
	v_mfma_f32_16x16x32_bf16 v[0:3], v[176:179], v[208:211], v[0:3]
	v_mfma_f32_16x16x32_bf16 v[0:3], v[180:183], v[212:215], v[0:3]
	s_setprio 0
	s_barrier
	s_add_i32 s56, 0, 0x18000
	s_add_i32 s57, 0, 0x1c000
	v_add_u32_e32 v164, s56, v155
	v_add_u32_e32 v180, s57, v155
	ds_read_b128 v[146:149], v164
	ds_read_b128 v[150:153], v164 offset:1024
	ds_read_b128 v[160:163], v164 offset:2048
	ds_read_b128 v[164:167], v164 offset:3072
	ds_read_b128 v[168:171], v180
	ds_read_b128 v[172:175], v180 offset:1024
	ds_read_b128 v[176:179], v180 offset:2048
	ds_read_b128 v[180:183], v180 offset:3072
	s_add_u32 s36, s36, 0x80000
	s_addc_u32 s37, s37, 0
	s_mov_b32 m0, s41
	v_lshl_add_u64 v[224:225], s[36:37], 0, v[136:137]
	ds_read_b128 v[184:187], v159 offset:32768
	ds_read_b128 v[188:191], v159 offset:33792
	ds_read_b128 v[192:195], v159 offset:34816
	ds_read_b128 v[196:199], v159 offset:35840
	ds_read_b128 v[200:203], v159 offset:36864
	ds_read_b128 v[204:207], v159 offset:37888
	ds_read_b128 v[208:211], v159 offset:38912
	ds_read_b128 v[212:215], v159 offset:39936
	global_load_lds_dwordx4 v[224:225], off
	v_lshl_add_u64 v[224:225], s[36:37], 0, v[132:133]
	s_mov_b32 m0, s42
	s_nop 0
	global_load_lds_dwordx4 v[224:225], off
	s_waitcnt vmcnt(8)
	s_waitcnt lgkmcnt(0)
	s_barrier
	s_setprio 1
	s_waitcnt lgkmcnt(0)
	v_mfma_f32_16x16x32_bf16 v[124:127], v[146:149], v[184:187], v[124:127]
	v_mfma_f32_16x16x32_bf16 v[124:127], v[150:153], v[188:191], v[124:127]
	v_mfma_f32_16x16x32_bf16 v[120:123], v[160:163], v[184:187], v[120:123]
	v_mfma_f32_16x16x32_bf16 v[120:123], v[164:167], v[188:191], v[120:123]
	v_mfma_f32_16x16x32_bf16 v[108:111], v[146:149], v[192:195], v[108:111]
	v_mfma_f32_16x16x32_bf16 v[108:111], v[150:153], v[196:199], v[108:111]
	v_mfma_f32_16x16x32_bf16 v[104:107], v[160:163], v[192:195], v[104:107]
	v_mfma_f32_16x16x32_bf16 v[104:107], v[164:167], v[196:199], v[104:107]
	v_mfma_f32_16x16x32_bf16 v[92:95], v[146:149], v[200:203], v[92:95]
	v_mfma_f32_16x16x32_bf16 v[92:95], v[150:153], v[204:207], v[92:95]
	v_mfma_f32_16x16x32_bf16 v[88:91], v[160:163], v[200:203], v[88:91]
	v_mfma_f32_16x16x32_bf16 v[88:91], v[164:167], v[204:207], v[88:91]
	v_mfma_f32_16x16x32_bf16 v[76:79], v[146:149], v[208:211], v[76:79]
	v_mfma_f32_16x16x32_bf16 v[76:79], v[150:153], v[212:215], v[76:79]
	v_mfma_f32_16x16x32_bf16 v[72:75], v[160:163], v[208:211], v[72:75]
	v_mfma_f32_16x16x32_bf16 v[72:75], v[164:167], v[212:215], v[72:75]
	s_setprio 0
	s_setprio 1
	v_mfma_f32_16x16x32_bf16 v[116:119], v[168:171], v[184:187], v[116:119]
	v_mfma_f32_16x16x32_bf16 v[116:119], v[172:175], v[188:191], v[116:119]
	v_mfma_f32_16x16x32_bf16 v[112:115], v[176:179], v[184:187], v[112:115]
	v_mfma_f32_16x16x32_bf16 v[112:115], v[180:183], v[188:191], v[112:115]
	v_mfma_f32_16x16x32_bf16 v[100:103], v[168:171], v[192:195], v[100:103]
	v_mfma_f32_16x16x32_bf16 v[100:103], v[172:175], v[196:199], v[100:103]
	v_mfma_f32_16x16x32_bf16 v[96:99], v[176:179], v[192:195], v[96:99]
	v_mfma_f32_16x16x32_bf16 v[96:99], v[180:183], v[196:199], v[96:99]
	v_mfma_f32_16x16x32_bf16 v[84:87], v[168:171], v[200:203], v[84:87]
	v_mfma_f32_16x16x32_bf16 v[84:87], v[172:175], v[204:207], v[84:87]
	v_mfma_f32_16x16x32_bf16 v[80:83], v[176:179], v[200:203], v[80:83]
	v_mfma_f32_16x16x32_bf16 v[80:83], v[180:183], v[204:207], v[80:83]
	v_mfma_f32_16x16x32_bf16 v[68:71], v[168:171], v[208:211], v[68:71]
	v_mfma_f32_16x16x32_bf16 v[68:71], v[172:175], v[212:215], v[68:71]
	v_mfma_f32_16x16x32_bf16 v[64:67], v[176:179], v[208:211], v[64:67]
	v_mfma_f32_16x16x32_bf16 v[64:67], v[180:183], v[212:215], v[64:67]
	s_setprio 0
	s_barrier
	s_add_i32 s36, s56, s33
	v_lshl_add_u64 v[216:217], v[216:217], 0, s[14:15]
	s_mov_b32 m0, s36
	ds_read_b128 v[184:187], v159 offset:49152
	ds_read_b128 v[188:191], v159 offset:50176
	ds_read_b128 v[192:195], v159 offset:51200
	ds_read_b128 v[196:199], v159 offset:52224
	ds_read_b128 v[200:203], v159 offset:53248
	ds_read_b128 v[204:207], v159 offset:54272
	ds_read_b128 v[208:211], v159 offset:55296
	ds_read_b128 v[212:215], v159 offset:56320
	global_load_lds_dwordx4 v[216:217], off
	s_add_i32 m0, s36, 0x2000
	s_add_u32 s34, s34, 0x80080
	v_lshl_add_u64 v[216:217], v[218:219], 0, s[14:15]
	s_addc_u32 s35, s35, 0
	s_add_i32 s36, s57, s33
	global_load_lds_dwordx4 v[216:217], off
	v_lshl_add_u64 v[216:217], s[34:35], 0, v[134:135]
	s_mov_b32 m0, s36
	s_nop 0
	global_load_lds_dwordx4 v[216:217], off
	v_lshl_add_u64 v[216:217], s[34:35], 0, v[130:131]
	s_add_i32 m0, s36, 0x2000
	s_nop 0
	global_load_lds_dwordx4 v[216:217], off
	v_lshl_add_u64 v[216:217], v[220:221], 0, s[14:15]
	s_mov_b32 m0, s44
	s_nop 0
	global_load_lds_dwordx4 v[216:217], off
	v_lshl_add_u64 v[216:217], v[222:223], 0, s[14:15]
	s_mov_b32 m0, s45
	s_nop 0
	global_load_lds_dwordx4 v[216:217], off
	s_waitcnt vmcnt(8)
	s_waitcnt lgkmcnt(0)
	s_barrier
	s_setprio 1
	s_waitcnt lgkmcnt(0)
	v_mfma_f32_16x16x32_bf16 v[60:63], v[146:149], v[184:187], v[60:63]
	v_mfma_f32_16x16x32_bf16 v[60:63], v[150:153], v[188:191], v[60:63]
	v_mfma_f32_16x16x32_bf16 v[56:59], v[160:163], v[184:187], v[56:59]
	v_mfma_f32_16x16x32_bf16 v[56:59], v[164:167], v[188:191], v[56:59]
	v_mfma_f32_16x16x32_bf16 v[44:47], v[146:149], v[192:195], v[44:47]
	v_mfma_f32_16x16x32_bf16 v[44:47], v[150:153], v[196:199], v[44:47]
	v_mfma_f32_16x16x32_bf16 v[40:43], v[160:163], v[192:195], v[40:43]
	v_mfma_f32_16x16x32_bf16 v[40:43], v[164:167], v[196:199], v[40:43]
	v_mfma_f32_16x16x32_bf16 v[28:31], v[146:149], v[200:203], v[28:31]
	v_mfma_f32_16x16x32_bf16 v[28:31], v[150:153], v[204:207], v[28:31]
	v_mfma_f32_16x16x32_bf16 v[24:27], v[160:163], v[200:203], v[24:27]
	v_mfma_f32_16x16x32_bf16 v[24:27], v[164:167], v[204:207], v[24:27]
	v_mfma_f32_16x16x32_bf16 v[12:15], v[146:149], v[208:211], v[12:15]
	v_mfma_f32_16x16x32_bf16 v[12:15], v[150:153], v[212:215], v[12:15]
	v_mfma_f32_16x16x32_bf16 v[8:11], v[160:163], v[208:211], v[8:11]
	v_mfma_f32_16x16x32_bf16 v[8:11], v[164:167], v[212:215], v[8:11]
	s_setprio 0
	s_setprio 1
	v_mfma_f32_16x16x32_bf16 v[52:55], v[168:171], v[184:187], v[52:55]
	v_mfma_f32_16x16x32_bf16 v[52:55], v[172:175], v[188:191], v[52:55]
	v_mfma_f32_16x16x32_bf16 v[48:51], v[176:179], v[184:187], v[48:51]
	v_mfma_f32_16x16x32_bf16 v[48:51], v[180:183], v[188:191], v[48:51]
	v_mfma_f32_16x16x32_bf16 v[36:39], v[168:171], v[192:195], v[36:39]
	v_mfma_f32_16x16x32_bf16 v[36:39], v[172:175], v[196:199], v[36:39]
	v_mfma_f32_16x16x32_bf16 v[32:35], v[176:179], v[192:195], v[32:35]
	v_mfma_f32_16x16x32_bf16 v[32:35], v[180:183], v[196:199], v[32:35]
	v_mfma_f32_16x16x32_bf16 v[20:23], v[168:171], v[200:203], v[20:23]
	v_mfma_f32_16x16x32_bf16 v[20:23], v[172:175], v[204:207], v[20:23]
	v_mfma_f32_16x16x32_bf16 v[16:19], v[176:179], v[200:203], v[16:19]
	v_mfma_f32_16x16x32_bf16 v[16:19], v[180:183], v[204:207], v[16:19]
	v_mfma_f32_16x16x32_bf16 v[4:7], v[168:171], v[208:211], v[4:7]
	v_mfma_f32_16x16x32_bf16 v[4:7], v[172:175], v[212:215], v[4:7]
	v_mfma_f32_16x16x32_bf16 v[0:3], v[176:179], v[208:211], v[0:3]
	v_mfma_f32_16x16x32_bf16 v[0:3], v[180:183], v[212:215], v[0:3]
	s_setprio 0
	s_barrier
	s_add_i32 s55, s55, 2
	s_add_u32 s30, s30, 0x100
	s_addc_u32 s31, s31, 0
	s_add_u32 s53, s53, 0x100
	s_addc_u32 s54, s54, 0
	s_cmp_gt_u32 s55, 29
	s_cbranch_scc0 .LBB0_131
	s_and_b64 vcc, exec, s[18:19]
	s_cbranch_vccz .LBB0_134
	s_barrier

.LBB0_585:
	v_add_u32_e32 v166, s42, v152
	v_add_u32_e32 v182, s43, v152
	s_add_u32 s26, s12, s24
	ds_read_b128 v[154:157], v166
	ds_read_b128 v[158:161], v166 offset:1024
	ds_read_b128 v[162:165], v166 offset:2048
	ds_read_b128 v[166:169], v166 offset:3072
	ds_read_b128 v[170:173], v182
	ds_read_b128 v[174:177], v182 offset:1024
	ds_read_b128 v[178:181], v182 offset:2048
	ds_read_b128 v[182:185], v182 offset:3072
	s_addc_u32 s27, s13, s25
	s_add_u32 s26, s26, 0x100
	s_addc_u32 s27, s27, 0
	s_add_u32 s50, s45, s24
	s_addc_u32 s51, s46, s25
	s_cmpk_eq_i32 s24, 0xf00
	s_cselect_b32 s29, s19, s27
	s_cselect_b32 s28, s47, s26
	s_cselect_b32 s27, s17, s51
	s_cselect_b32 s26, s48, s50
	v_lshl_add_u64 v[218:219], v[146:147], 0, s[24:25]
	s_add_i32 m0, s11, 0xc000
	ds_read_b128 v[186:189], v153
	ds_read_b128 v[190:193], v153 offset:1024
	ds_read_b128 v[194:197], v153 offset:2048
	ds_read_b128 v[198:201], v153 offset:3072
	ds_read_b128 v[202:205], v153 offset:4096
	ds_read_b128 v[206:209], v153 offset:5120
	ds_read_b128 v[210:213], v153 offset:6144
	ds_read_b128 v[214:217], v153 offset:7168
	global_load_lds_dwordx4 v[218:219], off
	v_lshl_add_u64 v[218:219], v[148:149], 0, s[24:25]
	s_add_i32 m0, s11, 0xe000
	s_nop 0
	global_load_lds_dwordx4 v[218:219], off
	s_waitcnt vmcnt(8)
	s_waitcnt lgkmcnt(0)
	s_barrier
	s_setprio 1
	s_waitcnt lgkmcnt(0)
	v_mfma_f32_16x16x32_bf16 v[124:127], v[154:157], v[186:189], v[124:127]
	v_mfma_f32_16x16x32_bf16 v[124:127], v[158:161], v[190:193], v[124:127]
	v_mfma_f32_16x16x32_bf16 v[120:123], v[162:165], v[186:189], v[120:123]
	v_mfma_f32_16x16x32_bf16 v[120:123], v[166:169], v[190:193], v[120:123]
	v_mfma_f32_16x16x32_bf16 v[108:111], v[154:157], v[194:197], v[108:111]
	v_mfma_f32_16x16x32_bf16 v[108:111], v[158:161], v[198:201], v[108:111]
	v_mfma_f32_16x16x32_bf16 v[104:107], v[162:165], v[194:197], v[104:107]
	v_mfma_f32_16x16x32_bf16 v[104:107], v[166:169], v[198:201], v[104:107]
	v_mfma_f32_16x16x32_bf16 v[92:95], v[154:157], v[202:205], v[92:95]
	v_mfma_f32_16x16x32_bf16 v[92:95], v[158:161], v[206:209], v[92:95]
	v_mfma_f32_16x16x32_bf16 v[88:91], v[162:165], v[202:205], v[88:91]
	v_mfma_f32_16x16x32_bf16 v[88:91], v[166:169], v[206:209], v[88:91]
	v_mfma_f32_16x16x32_bf16 v[76:79], v[154:157], v[210:213], v[76:79]
	v_mfma_f32_16x16x32_bf16 v[76:79], v[158:161], v[214:217], v[76:79]
	v_mfma_f32_16x16x32_bf16 v[72:75], v[162:165], v[210:213], v[72:75]
	v_mfma_f32_16x16x32_bf16 v[72:75], v[166:169], v[214:217], v[72:75]
	s_setprio 0
	s_setprio 1
	v_mfma_f32_16x16x32_bf16 v[116:119], v[170:173], v[186:189], v[116:119]
	v_mfma_f32_16x16x32_bf16 v[116:119], v[174:177], v[190:193], v[116:119]
	v_mfma_f32_16x16x32_bf16 v[112:115], v[178:181], v[186:189], v[112:115]
	v_mfma_f32_16x16x32_bf16 v[112:115], v[182:185], v[190:193], v[112:115]
	v_mfma_f32_16x16x32_bf16 v[100:103], v[170:173], v[194:197], v[100:103]
	v_mfma_f32_16x16x32_bf16 v[100:103], v[174:177], v[198:201], v[100:103]
	v_mfma_f32_16x16x32_bf16 v[96:99], v[178:181], v[194:197], v[96:99]
	v_mfma_f32_16x16x32_bf16 v[96:99], v[182:185], v[198:201], v[96:99]
	v_mfma_f32_16x16x32_bf16 v[84:87], v[170:173], v[202:205], v[84:87]
	v_mfma_f32_16x16x32_bf16 v[84:87], v[174:177], v[206:209], v[84:87]
	v_mfma_f32_16x16x32_bf16 v[80:83], v[178:181], v[202:205], v[80:83]
	v_mfma_f32_16x16x32_bf16 v[80:83], v[182:185], v[206:209], v[80:83]
	v_mfma_f32_16x16x32_bf16 v[68:71], v[170:173], v[210:213], v[68:71]
	v_mfma_f32_16x16x32_bf16 v[68:71], v[174:177], v[214:217], v[68:71]
	v_mfma_f32_16x16x32_bf16 v[64:67], v[178:181], v[210:213], v[64:67]
	v_mfma_f32_16x16x32_bf16 v[64:67], v[182:185], v[214:217], v[64:67]
	s_setprio 0
	s_barrier
	s_add_i32 s50, s42, s35
	v_lshl_add_u64 v[218:219], s[26:27], 0, v[132:133]
	s_mov_b32 m0, s50
	ds_read_b128 v[186:189], v153 offset:16384
	ds_read_b128 v[190:193], v153 offset:17408
	ds_read_b128 v[194:197], v153 offset:18432
	ds_read_b128 v[198:201], v153 offset:19456
	ds_read_b128 v[202:205], v153 offset:20480
	ds_read_b128 v[206:209], v153 offset:21504
	ds_read_b128 v[210:213], v153 offset:22528
	ds_read_b128 v[214:217], v153 offset:23552
	global_load_lds_dwordx4 v[218:219], off
	s_add_i32 m0, s50, 0x2000
	s_add_u32 s50, s26, 0x80000
	v_lshl_add_u64 v[220:221], s[26:27], 0, v[136:137]
	s_addc_u32 s51, s27, 0
	s_add_i32 s52, s43, s35
	global_load_lds_dwordx4 v[220:221], off
	v_lshl_add_u64 v[222:223], s[50:51], 0, v[132:133]
	s_mov_b32 m0, s52
	v_lshl_add_u64 v[224:225], s[28:29], 0, v[134:135]
	global_load_lds_dwordx4 v[222:223], off
	v_lshl_add_u64 v[222:223], s[50:51], 0, v[136:137]
	s_add_i32 m0, s52, 0x2000
	s_nop 0
	global_load_lds_dwordx4 v[222:223], off
	v_lshl_add_u64 v[222:223], s[28:29], 0, v[130:131]
	s_mov_b32 m0, s11
	s_nop 0
	global_load_lds_dwordx4 v[222:223], off
	s_mov_b32 m0, s36
	s_nop 0
	global_load_lds_dwordx4 v[224:225], off
	s_waitcnt vmcnt(8)
	s_waitcnt lgkmcnt(0)
	s_barrier
	s_setprio 1
	s_waitcnt lgkmcnt(0)
	v_mfma_f32_16x16x32_bf16 v[60:63], v[154:157], v[186:189], v[60:63]
	v_mfma_f32_16x16x32_bf16 v[60:63], v[158:161], v[190:193], v[60:63]
	v_mfma_f32_16x16x32_bf16 v[56:59], v[162:165], v[186:189], v[56:59]
	v_mfma_f32_16x16x32_bf16 v[56:59], v[166:169], v[190:193], v[56:59]
	v_mfma_f32_16x16x32_bf16 v[44:47], v[154:157], v[194:197], v[44:47]
	v_mfma_f32_16x16x32_bf16 v[44:47], v[158:161], v[198:201], v[44:47]
	v_mfma_f32_16x16x32_bf16 v[40:43], v[162:165], v[194:197], v[40:43]
	v_mfma_f32_16x16x32_bf16 v[40:43], v[166:169], v[198:201], v[40:43]
	v_mfma_f32_16x16x32_bf16 v[28:31], v[154:157], v[202:205], v[28:31]
	v_mfma_f32_16x16x32_bf16 v[28:31], v[158:161], v[206:209], v[28:31]
	v_mfma_f32_16x16x32_bf16 v[24:27], v[162:165], v[202:205], v[24:27]
	v_mfma_f32_16x16x32_bf16 v[24:27], v[166:169], v[206:209], v[24:27]
	v_mfma_f32_16x16x32_bf16 v[12:15], v[154:157], v[210:213], v[12:15]
	v_mfma_f32_16x16x32_bf16 v[12:15], v[158:161], v[214:217], v[12:15]
	v_mfma_f32_16x16x32_bf16 v[8:11], v[162:165], v[210:213], v[8:11]
	v_mfma_f32_16x16x32_bf16 v[8:11], v[166:169], v[214:217], v[8:11]
	s_setprio 0
	s_setprio 1
	v_mfma_f32_16x16x32_bf16 v[52:55], v[170:173], v[186:189], v[52:55]
	v_mfma_f32_16x16x32_bf16 v[52:55], v[174:177], v[190:193], v[52:55]
	v_mfma_f32_16x16x32_bf16 v[48:51], v[178:181], v[186:189], v[48:51]
	v_mfma_f32_16x16x32_bf16 v[48:51], v[182:185], v[190:193], v[48:51]
	v_mfma_f32_16x16x32_bf16 v[36:39], v[170:173], v[194:197], v[36:39]
	v_mfma_f32_16x16x32_bf16 v[36:39], v[174:177], v[198:201], v[36:39]
	v_mfma_f32_16x16x32_bf16 v[32:35], v[178:181], v[194:197], v[32:35]
	v_mfma_f32_16x16x32_bf16 v[32:35], v[182:185], v[198:201], v[32:35]
	v_mfma_f32_16x16x32_bf16 v[20:23], v[170:173], v[202:205], v[20:23]
	v_mfma_f32_16x16x32_bf16 v[20:23], v[174:177], v[206:209], v[20:23]
	v_mfma_f32_16x16x32_bf16 v[16:19], v[178:181], v[202:205], v[16:19]
	v_mfma_f32_16x16x32_bf16 v[16:19], v[182:185], v[206:209], v[16:19]
	v_mfma_f32_16x16x32_bf16 v[4:7], v[170:173], v[210:213], v[4:7]
	v_mfma_f32_16x16x32_bf16 v[4:7], v[174:177], v[214:217], v[4:7]
	v_mfma_f32_16x16x32_bf16 v[0:3], v[178:181], v[210:213], v[0:3]
	v_mfma_f32_16x16x32_bf16 v[0:3], v[182:185], v[214:217], v[0:3]
	s_setprio 0
	s_barrier
	s_add_i32 s50, 0, 0x18000
	s_add_i32 s51, 0, 0x1c000
	v_add_u32_e32 v166, s50, v152
	v_add_u32_e32 v182, s51, v152
	ds_read_b128 v[154:157], v166
	ds_read_b128 v[158:161], v166 offset:1024
	ds_read_b128 v[162:165], v166 offset:2048
	ds_read_b128 v[166:169], v166 offset:3072
	ds_read_b128 v[170:173], v182
	ds_read_b128 v[174:177], v182 offset:1024
	ds_read_b128 v[178:181], v182 offset:2048
	ds_read_b128 v[182:185], v182 offset:3072
	s_add_u32 s28, s28, 0x80000
	s_addc_u32 s29, s29, 0
	s_mov_b32 m0, s37
	v_lshl_add_u64 v[226:227], s[28:29], 0, v[130:131]
	ds_read_b128 v[186:189], v153 offset:32768
	ds_read_b128 v[190:193], v153 offset:33792
	ds_read_b128 v[194:197], v153 offset:34816
	ds_read_b128 v[198:201], v153 offset:35840
	ds_read_b128 v[202:205], v153 offset:36864
	ds_read_b128 v[206:209], v153 offset:37888
	ds_read_b128 v[210:213], v153 offset:38912
	ds_read_b128 v[214:217], v153 offset:39936
	global_load_lds_dwordx4 v[226:227], off
	v_lshl_add_u64 v[226:227], s[28:29], 0, v[134:135]
	s_mov_b32 m0, s38
	s_nop 0
	global_load_lds_dwordx4 v[226:227], off
	s_waitcnt vmcnt(8)
	s_waitcnt lgkmcnt(0)
	s_barrier
	s_setprio 1
	s_waitcnt lgkmcnt(0)
	v_mfma_f32_16x16x32_bf16 v[124:127], v[154:157], v[186:189], v[124:127]
	v_mfma_f32_16x16x32_bf16 v[124:127], v[158:161], v[190:193], v[124:127]
	v_mfma_f32_16x16x32_bf16 v[120:123], v[162:165], v[186:189], v[120:123]
	v_mfma_f32_16x16x32_bf16 v[120:123], v[166:169], v[190:193], v[120:123]
	v_mfma_f32_16x16x32_bf16 v[108:111], v[154:157], v[194:197], v[108:111]
	v_mfma_f32_16x16x32_bf16 v[108:111], v[158:161], v[198:201], v[108:111]
	v_mfma_f32_16x16x32_bf16 v[104:107], v[162:165], v[194:197], v[104:107]
	v_mfma_f32_16x16x32_bf16 v[104:107], v[166:169], v[198:201], v[104:107]
	v_mfma_f32_16x16x32_bf16 v[92:95], v[154:157], v[202:205], v[92:95]
	v_mfma_f32_16x16x32_bf16 v[92:95], v[158:161], v[206:209], v[92:95]
	v_mfma_f32_16x16x32_bf16 v[88:91], v[162:165], v[202:205], v[88:91]
	v_mfma_f32_16x16x32_bf16 v[88:91], v[166:169], v[206:209], v[88:91]
	v_mfma_f32_16x16x32_bf16 v[76:79], v[154:157], v[210:213], v[76:79]
	v_mfma_f32_16x16x32_bf16 v[76:79], v[158:161], v[214:217], v[76:79]
	v_mfma_f32_16x16x32_bf16 v[72:75], v[162:165], v[210:213], v[72:75]
	v_mfma_f32_16x16x32_bf16 v[72:75], v[166:169], v[214:217], v[72:75]
	s_setprio 0
	s_setprio 1
	v_mfma_f32_16x16x32_bf16 v[116:119], v[170:173], v[186:189], v[116:119]
	v_mfma_f32_16x16x32_bf16 v[116:119], v[174:177], v[190:193], v[116:119]
	v_mfma_f32_16x16x32_bf16 v[112:115], v[178:181], v[186:189], v[112:115]
	v_mfma_f32_16x16x32_bf16 v[112:115], v[182:185], v[190:193], v[112:115]
	v_mfma_f32_16x16x32_bf16 v[100:103], v[170:173], v[194:197], v[100:103]
	v_mfma_f32_16x16x32_bf16 v[100:103], v[174:177], v[198:201], v[100:103]
	v_mfma_f32_16x16x32_bf16 v[96:99], v[178:181], v[194:197], v[96:99]
	v_mfma_f32_16x16x32_bf16 v[96:99], v[182:185], v[198:201], v[96:99]
	v_mfma_f32_16x16x32_bf16 v[84:87], v[170:173], v[202:205], v[84:87]
	v_mfma_f32_16x16x32_bf16 v[84:87], v[174:177], v[206:209], v[84:87]
	v_mfma_f32_16x16x32_bf16 v[80:83], v[178:181], v[202:205], v[80:83]
	v_mfma_f32_16x16x32_bf16 v[80:83], v[182:185], v[206:209], v[80:83]
	v_mfma_f32_16x16x32_bf16 v[68:71], v[170:173], v[210:213], v[68:71]
	v_mfma_f32_16x16x32_bf16 v[68:71], v[174:177], v[214:217], v[68:71]
	v_mfma_f32_16x16x32_bf16 v[64:67], v[178:181], v[210:213], v[64:67]
	v_mfma_f32_16x16x32_bf16 v[64:67], v[182:185], v[214:217], v[64:67]
	s_setprio 0
	s_barrier
	s_add_i32 s28, s50, s35
	v_lshl_add_u64 v[218:219], v[218:219], 0, s[14:15]
	s_mov_b32 m0, s28
	ds_read_b128 v[186:189], v153 offset:49152
	ds_read_b128 v[190:193], v153 offset:50176
	ds_read_b128 v[194:197], v153 offset:51200
	ds_read_b128 v[198:201], v153 offset:52224
	ds_read_b128 v[202:205], v153 offset:53248
	ds_read_b128 v[206:209], v153 offset:54272
	ds_read_b128 v[210:213], v153 offset:55296
	ds_read_b128 v[214:217], v153 offset:56320
	global_load_lds_dwordx4 v[218:219], off
	s_add_i32 m0, s28, 0x2000
	s_add_u32 s26, s26, 0x80080
	v_lshl_add_u64 v[218:219], v[220:221], 0, s[14:15]
	s_addc_u32 s27, s27, 0
	s_add_i32 s28, s51, s35
	global_load_lds_dwordx4 v[218:219], off
	v_lshl_add_u64 v[218:219], s[26:27], 0, v[132:133]
	s_mov_b32 m0, s28
	s_nop 0
	global_load_lds_dwordx4 v[218:219], off
	v_lshl_add_u64 v[218:219], s[26:27], 0, v[136:137]
	s_add_i32 m0, s28, 0x2000
	s_nop 0
	global_load_lds_dwordx4 v[218:219], off
	v_lshl_add_u64 v[218:219], v[222:223], 0, s[14:15]
	s_mov_b32 m0, s39
	s_nop 0
	global_load_lds_dwordx4 v[218:219], off
	v_lshl_add_u64 v[218:219], v[224:225], 0, s[14:15]
	s_mov_b32 m0, s40
	s_nop 0
	global_load_lds_dwordx4 v[218:219], off
	s_waitcnt vmcnt(8)
	s_waitcnt lgkmcnt(0)
	s_barrier
	s_setprio 1
	s_waitcnt lgkmcnt(0)
	v_mfma_f32_16x16x32_bf16 v[60:63], v[154:157], v[186:189], v[60:63]
	v_mfma_f32_16x16x32_bf16 v[60:63], v[158:161], v[190:193], v[60:63]
	v_mfma_f32_16x16x32_bf16 v[56:59], v[162:165], v[186:189], v[56:59]
	v_mfma_f32_16x16x32_bf16 v[56:59], v[166:169], v[190:193], v[56:59]
	v_mfma_f32_16x16x32_bf16 v[44:47], v[154:157], v[194:197], v[44:47]
	v_mfma_f32_16x16x32_bf16 v[44:47], v[158:161], v[198:201], v[44:47]
	v_mfma_f32_16x16x32_bf16 v[40:43], v[162:165], v[194:197], v[40:43]
	v_mfma_f32_16x16x32_bf16 v[40:43], v[166:169], v[198:201], v[40:43]
	v_mfma_f32_16x16x32_bf16 v[28:31], v[154:157], v[202:205], v[28:31]
	v_mfma_f32_16x16x32_bf16 v[28:31], v[158:161], v[206:209], v[28:31]
	v_mfma_f32_16x16x32_bf16 v[24:27], v[162:165], v[202:205], v[24:27]
	v_mfma_f32_16x16x32_bf16 v[24:27], v[166:169], v[206:209], v[24:27]
	v_mfma_f32_16x16x32_bf16 v[12:15], v[154:157], v[210:213], v[12:15]
	v_mfma_f32_16x16x32_bf16 v[12:15], v[158:161], v[214:217], v[12:15]
	v_mfma_f32_16x16x32_bf16 v[8:11], v[162:165], v[210:213], v[8:11]
	v_mfma_f32_16x16x32_bf16 v[8:11], v[166:169], v[214:217], v[8:11]
	s_setprio 0
	s_setprio 1
	v_mfma_f32_16x16x32_bf16 v[52:55], v[170:173], v[186:189], v[52:55]
	v_mfma_f32_16x16x32_bf16 v[52:55], v[174:177], v[190:193], v[52:55]
	v_mfma_f32_16x16x32_bf16 v[48:51], v[178:181], v[186:189], v[48:51]
	v_mfma_f32_16x16x32_bf16 v[48:51], v[182:185], v[190:193], v[48:51]
	v_mfma_f32_16x16x32_bf16 v[36:39], v[170:173], v[194:197], v[36:39]
	v_mfma_f32_16x16x32_bf16 v[36:39], v[174:177], v[198:201], v[36:39]
	v_mfma_f32_16x16x32_bf16 v[32:35], v[178:181], v[194:197], v[32:35]
	v_mfma_f32_16x16x32_bf16 v[32:35], v[182:185], v[198:201], v[32:35]
	v_mfma_f32_16x16x32_bf16 v[20:23], v[170:173], v[202:205], v[20:23]
	v_mfma_f32_16x16x32_bf16 v[20:23], v[174:177], v[206:209], v[20:23]
	v_mfma_f32_16x16x32_bf16 v[16:19], v[178:181], v[202:205], v[16:19]
	v_mfma_f32_16x16x32_bf16 v[16:19], v[182:185], v[206:209], v[16:19]
	v_mfma_f32_16x16x32_bf16 v[4:7], v[170:173], v[210:213], v[4:7]
	v_mfma_f32_16x16x32_bf16 v[4:7], v[174:177], v[214:217], v[4:7]
	v_mfma_f32_16x16x32_bf16 v[0:3], v[178:181], v[210:213], v[0:3]
	v_mfma_f32_16x16x32_bf16 v[0:3], v[182:185], v[214:217], v[0:3]
	s_setprio 0
	s_barrier
	s_add_i32 s49, s49, 2
	s_add_u32 s24, s24, 0x100
	s_addc_u32 s25, s25, 0
	s_cmp_gt_u32 s49, 29
	s_cbranch_scc0 .LBB0_585
	s_add_u32 s24, s45, 0xffffff00
	s_addc_u32 s25, s46, -1
	s_andn2_b64 vcc, exec, s[4:5]
	s_cbranch_vccnz .LBB0_588
	v_mov_b32_e32 v0, 0
	s_mov_b32 s8, s16
	s_mov_b32 s10, s18
	s_mov_b64 s[12:13], s[22:23]
	s_mov_b32 s41, s44
	v_mov_b32_e32 v1, v0
	v_mov_b32_e32 v2, v0
	v_mov_b32_e32 v3, v0
	v_mov_b32_e32 v4, v0
	v_mov_b32_e32 v5, v0
	v_mov_b32_e32 v6, v0
	v_mov_b32_e32 v7, v0
	v_mov_b32_e32 v16, v0
	v_mov_b32_e32 v17, v0
	v_mov_b32_e32 v18, v0
	v_mov_b32_e32 v19, v0
	v_mov_b32_e32 v20, v0
	v_mov_b32_e32 v21, v0
	v_mov_b32_e32 v22, v0
	v_mov_b32_e32 v23, v0
	v_mov_b32_e32 v32, v0
	v_mov_b32_e32 v33, v0
	v_mov_b32_e32 v34, v0
	v_mov_b32_e32 v35, v0
	v_mov_b32_e32 v36, v0
	v_mov_b32_e32 v37, v0
	v_mov_b32_e32 v38, v0
	v_mov_b32_e32 v39, v0
	v_mov_b32_e32 v48, v0
	v_mov_b32_e32 v49, v0
	v_mov_b32_e32 v50, v0
	v_mov_b32_e32 v51, v0
	v_mov_b32_e32 v52, v0
	v_mov_b32_e32 v53, v0
	v_mov_b32_e32 v54, v0
	v_mov_b32_e32 v55, v0
	v_mov_b32_e32 v8, v0
	v_mov_b32_e32 v9, v0
	v_mov_b32_e32 v10, v0
	v_mov_b32_e32 v11, v0
	v_mov_b32_e32 v12, v0
	v_mov_b32_e32 v13, v0
	v_mov_b32_e32 v14, v0
	v_mov_b32_e32 v15, v0
	v_mov_b32_e32 v24, v0
	v_mov_b32_e32 v25, v0
	v_mov_b32_e32 v26, v0
	v_mov_b32_e32 v27, v0
	v_mov_b32_e32 v28, v0
	v_mov_b32_e32 v29, v0
	v_mov_b32_e32 v30, v0
	v_mov_b32_e32 v31, v0
	v_mov_b32_e32 v40, v0
	v_mov_b32_e32 v41, v0
	v_mov_b32_e32 v42, v0
	v_mov_b32_e32 v43, v0
	v_mov_b32_e32 v44, v0
	v_mov_b32_e32 v45, v0
	v_mov_b32_e32 v46, v0
	v_mov_b32_e32 v47, v0
	v_mov_b32_e32 v56, v0
	v_mov_b32_e32 v57, v0
	v_mov_b32_e32 v58, v0
	v_mov_b32_e32 v59, v0
	v_mov_b32_e32 v60, v0
	v_mov_b32_e32 v61, v0
	v_mov_b32_e32 v62, v0
	v_mov_b32_e32 v63, v0
	v_mov_b32_e32 v64, v0
	v_mov_b32_e32 v65, v0
	v_mov_b32_e32 v66, v0
	v_mov_b32_e32 v67, v0
	v_mov_b32_e32 v68, v0
	v_mov_b32_e32 v69, v0
	v_mov_b32_e32 v70, v0
	v_mov_b32_e32 v71, v0
	v_mov_b32_e32 v80, v0
	v_mov_b32_e32 v81, v0
	v_mov_b32_e32 v82, v0
	v_mov_b32_e32 v83, v0
	v_mov_b32_e32 v84, v0
	v_mov_b32_e32 v85, v0
	v_mov_b32_e32 v86, v0
	v_mov_b32_e32 v87, v0
	v_mov_b32_e32 v96, v0
	v_mov_b32_e32 v97, v0
	v_mov_b32_e32 v98, v0
	v_mov_b32_e32 v99, v0
	v_mov_b32_e32 v100, v0
	v_mov_b32_e32 v101, v0
	v_mov_b32_e32 v102, v0
	v_mov_b32_e32 v103, v0
	v_mov_b32_e32 v112, v0
	v_mov_b32_e32 v113, v0
	v_mov_b32_e32 v114, v0
	v_mov_b32_e32 v115, v0
	v_mov_b32_e32 v116, v0
	v_mov_b32_e32 v117, v0
	v_mov_b32_e32 v118, v0
	v_mov_b32_e32 v119, v0
	v_mov_b32_e32 v72, v0
	v_mov_b32_e32 v73, v0
	v_mov_b32_e32 v74, v0
	v_mov_b32_e32 v75, v0
	v_mov_b32_e32 v76, v0
	v_mov_b32_e32 v77, v0
	v_mov_b32_e32 v78, v0
	v_mov_b32_e32 v79, v0
	v_mov_b32_e32 v88, v0
	v_mov_b32_e32 v89, v0
	v_mov_b32_e32 v90, v0
	v_mov_b32_e32 v91, v0
	v_mov_b32_e32 v92, v0
	v_mov_b32_e32 v93, v0
	v_mov_b32_e32 v94, v0
	v_mov_b32_e32 v95, v0
	v_mov_b32_e32 v104, v0
	v_mov_b32_e32 v105, v0
	v_mov_b32_e32 v106, v0
	v_mov_b32_e32 v107, v0
	v_mov_b32_e32 v108, v0
	v_mov_b32_e32 v109, v0
	v_mov_b32_e32 v110, v0
	v_mov_b32_e32 v111, v0
	v_mov_b32_e32 v120, v0
	v_mov_b32_e32 v121, v0
	v_mov_b32_e32 v122, v0
	v_mov_b32_e32 v123, v0
	v_mov_b32_e32 v124, v0
	v_mov_b32_e32 v125, v0
	v_mov_b32_e32 v126, v0
	v_mov_b32_e32 v127, v0
	s_andn2_b64 vcc, exec, s[0:1]
	s_cbranch_vccnz .LBB0_589
	s_branch .LBB0_590

.LBB0_671:
	ds_read_b128 v[156:159], v151
	ds_read_b128 v[160:163], v151 offset:1024
	ds_read_b128 v[164:167], v151 offset:2048
	ds_read_b128 v[168:171], v151 offset:3072
	ds_read_b128 v[172:175], v152
	ds_read_b128 v[176:179], v152 offset:1024
	ds_read_b128 v[180:183], v152 offset:2048
	ds_read_b128 v[184:187], v152 offset:3072
	s_add_u32 s28, s26, 0xfff80080
	s_addc_u32 s29, s27, -1
	s_cmp_eq_u32 s53, 28
	s_cselect_b32 s31, s19, s29
	s_cselect_b32 s30, s49, s28
	s_cselect_b32 s29, s17, s52
	s_cselect_b32 s28, s50, s51
	v_lshl_add_u64 v[146:147], s[26:27], 0, v[138:139]
	s_add_i32 m0, s25, 0xc000
	ds_read_b128 v[188:191], v153
	ds_read_b128 v[192:195], v153 offset:1024
	ds_read_b128 v[196:199], v153 offset:2048
	ds_read_b128 v[200:203], v153 offset:3072
	ds_read_b128 v[204:207], v153 offset:4096
	ds_read_b128 v[208:211], v153 offset:5120
	ds_read_b128 v[212:215], v153 offset:6144
	ds_read_b128 v[216:219], v153 offset:7168
	global_load_lds_dwordx4 v[146:147], off
	v_lshl_add_u64 v[146:147], s[26:27], 0, v[140:141]
	s_add_i32 m0, s25, 0xe000
	s_nop 0
	global_load_lds_dwordx4 v[146:147], off
	s_waitcnt vmcnt(8)
	s_waitcnt lgkmcnt(0)
	s_barrier
	s_setprio 1
	s_waitcnt lgkmcnt(0)
	v_mfma_f32_16x16x32_bf16 v[116:119], v[156:159], v[188:191], v[116:119]
	v_mfma_f32_16x16x32_bf16 v[116:119], v[160:163], v[192:195], v[116:119]
	v_mfma_f32_16x16x32_bf16 v[112:115], v[164:167], v[188:191], v[112:115]
	v_mfma_f32_16x16x32_bf16 v[112:115], v[168:171], v[192:195], v[112:115]
	v_mfma_f32_16x16x32_bf16 v[100:103], v[156:159], v[196:199], v[100:103]
	v_mfma_f32_16x16x32_bf16 v[100:103], v[160:163], v[200:203], v[100:103]
	v_mfma_f32_16x16x32_bf16 v[96:99], v[164:167], v[196:199], v[96:99]
	v_mfma_f32_16x16x32_bf16 v[96:99], v[168:171], v[200:203], v[96:99]
	v_mfma_f32_16x16x32_bf16 v[84:87], v[156:159], v[204:207], v[84:87]
	v_mfma_f32_16x16x32_bf16 v[84:87], v[160:163], v[208:211], v[84:87]
	v_mfma_f32_16x16x32_bf16 v[80:83], v[164:167], v[204:207], v[80:83]
	v_mfma_f32_16x16x32_bf16 v[80:83], v[168:171], v[208:211], v[80:83]
	v_mfma_f32_16x16x32_bf16 v[68:71], v[156:159], v[212:215], v[68:71]
	v_mfma_f32_16x16x32_bf16 v[68:71], v[160:163], v[216:219], v[68:71]
	v_mfma_f32_16x16x32_bf16 v[64:67], v[164:167], v[212:215], v[64:67]
	v_mfma_f32_16x16x32_bf16 v[64:67], v[168:171], v[216:219], v[64:67]
	s_setprio 0
	s_setprio 1
	v_mfma_f32_16x16x32_bf16 v[124:127], v[172:175], v[188:191], v[124:127]
	v_mfma_f32_16x16x32_bf16 v[124:127], v[176:179], v[192:195], v[124:127]
	v_mfma_f32_16x16x32_bf16 v[120:123], v[180:183], v[188:191], v[120:123]
	v_mfma_f32_16x16x32_bf16 v[120:123], v[184:187], v[192:195], v[120:123]
	v_mfma_f32_16x16x32_bf16 v[108:111], v[172:175], v[196:199], v[108:111]
	v_mfma_f32_16x16x32_bf16 v[108:111], v[176:179], v[200:203], v[108:111]
	v_mfma_f32_16x16x32_bf16 v[104:107], v[180:183], v[196:199], v[104:107]
	v_mfma_f32_16x16x32_bf16 v[104:107], v[184:187], v[200:203], v[104:107]
	v_mfma_f32_16x16x32_bf16 v[92:95], v[172:175], v[204:207], v[92:95]
	v_mfma_f32_16x16x32_bf16 v[92:95], v[176:179], v[208:211], v[92:95]
	v_mfma_f32_16x16x32_bf16 v[88:91], v[180:183], v[204:207], v[88:91]
	v_mfma_f32_16x16x32_bf16 v[88:91], v[184:187], v[208:211], v[88:91]
	v_mfma_f32_16x16x32_bf16 v[76:79], v[172:175], v[212:215], v[76:79]
	v_mfma_f32_16x16x32_bf16 v[76:79], v[176:179], v[216:219], v[76:79]
	v_mfma_f32_16x16x32_bf16 v[72:75], v[180:183], v[212:215], v[72:75]
	v_mfma_f32_16x16x32_bf16 v[72:75], v[184:187], v[216:219], v[72:75]
	s_setprio 0
	s_barrier
	s_add_i32 s54, s46, s36
	v_lshl_add_u64 v[146:147], s[28:29], 0, v[134:135]
	s_mov_b32 m0, s54
	ds_read_b128 v[188:191], v153 offset:16384
	ds_read_b128 v[192:195], v153 offset:17408
	ds_read_b128 v[196:199], v153 offset:18432
	ds_read_b128 v[200:203], v153 offset:19456
	ds_read_b128 v[204:207], v153 offset:20480
	ds_read_b128 v[208:211], v153 offset:21504
	ds_read_b128 v[212:215], v153 offset:22528
	ds_read_b128 v[216:219], v153 offset:23552
	global_load_lds_dwordx4 v[146:147], off
	s_add_i32 m0, s54, 0x2000
	s_add_u32 s54, s28, 0x80000
	v_lshl_add_u64 v[220:221], s[28:29], 0, v[130:131]
	s_addc_u32 s55, s29, 0
	s_add_i32 s56, s47, s36
	global_load_lds_dwordx4 v[220:221], off
	v_lshl_add_u64 v[222:223], s[54:55], 0, v[134:135]
	s_mov_b32 m0, s56
	v_lshl_add_u64 v[224:225], s[30:31], 0, v[132:133]
	global_load_lds_dwordx4 v[222:223], off
	v_lshl_add_u64 v[222:223], s[54:55], 0, v[130:131]
	s_add_i32 m0, s56, 0x2000
	s_nop 0
	global_load_lds_dwordx4 v[222:223], off
	v_lshl_add_u64 v[222:223], s[30:31], 0, v[136:137]
	s_mov_b32 m0, s25
	s_nop 0
	global_load_lds_dwordx4 v[222:223], off
	s_mov_b32 m0, s39
	s_nop 0
	global_load_lds_dwordx4 v[224:225], off
	s_waitcnt vmcnt(8)
	s_waitcnt lgkmcnt(0)
	s_barrier
	s_setprio 1
	s_waitcnt lgkmcnt(0)
	v_mfma_f32_16x16x32_bf16 v[52:55], v[156:159], v[188:191], v[52:55]
	v_mfma_f32_16x16x32_bf16 v[52:55], v[160:163], v[192:195], v[52:55]
	v_mfma_f32_16x16x32_bf16 v[48:51], v[164:167], v[188:191], v[48:51]
	v_mfma_f32_16x16x32_bf16 v[48:51], v[168:171], v[192:195], v[48:51]
	v_mfma_f32_16x16x32_bf16 v[36:39], v[156:159], v[196:199], v[36:39]
	v_mfma_f32_16x16x32_bf16 v[36:39], v[160:163], v[200:203], v[36:39]
	v_mfma_f32_16x16x32_bf16 v[32:35], v[164:167], v[196:199], v[32:35]
	v_mfma_f32_16x16x32_bf16 v[32:35], v[168:171], v[200:203], v[32:35]
	v_mfma_f32_16x16x32_bf16 v[20:23], v[156:159], v[204:207], v[20:23]
	v_mfma_f32_16x16x32_bf16 v[20:23], v[160:163], v[208:211], v[20:23]
	v_mfma_f32_16x16x32_bf16 v[16:19], v[164:167], v[204:207], v[16:19]
	v_mfma_f32_16x16x32_bf16 v[16:19], v[168:171], v[208:211], v[16:19]
	v_mfma_f32_16x16x32_bf16 v[8:11], v[156:159], v[212:215], v[8:11]
	v_mfma_f32_16x16x32_bf16 v[8:11], v[160:163], v[216:219], v[8:11]
	v_mfma_f32_16x16x32_bf16 v[0:3], v[164:167], v[212:215], v[0:3]
	v_mfma_f32_16x16x32_bf16 v[0:3], v[168:171], v[216:219], v[0:3]
	s_setprio 0
	s_setprio 1
	v_mfma_f32_16x16x32_bf16 v[60:63], v[172:175], v[188:191], v[60:63]
	v_mfma_f32_16x16x32_bf16 v[60:63], v[176:179], v[192:195], v[60:63]
	v_mfma_f32_16x16x32_bf16 v[56:59], v[180:183], v[188:191], v[56:59]
	v_mfma_f32_16x16x32_bf16 v[56:59], v[184:187], v[192:195], v[56:59]
	v_mfma_f32_16x16x32_bf16 v[44:47], v[172:175], v[196:199], v[44:47]
	v_mfma_f32_16x16x32_bf16 v[44:47], v[176:179], v[200:203], v[44:47]
	v_mfma_f32_16x16x32_bf16 v[40:43], v[180:183], v[196:199], v[40:43]
	v_mfma_f32_16x16x32_bf16 v[40:43], v[184:187], v[200:203], v[40:43]
	v_mfma_f32_16x16x32_bf16 v[28:31], v[172:175], v[204:207], v[28:31]
	v_mfma_f32_16x16x32_bf16 v[28:31], v[176:179], v[208:211], v[28:31]
	v_mfma_f32_16x16x32_bf16 v[24:27], v[180:183], v[204:207], v[24:27]
	v_mfma_f32_16x16x32_bf16 v[24:27], v[184:187], v[208:211], v[24:27]
	v_mfma_f32_16x16x32_bf16 v[12:15], v[172:175], v[212:215], v[12:15]
	v_mfma_f32_16x16x32_bf16 v[12:15], v[176:179], v[216:219], v[12:15]
	v_mfma_f32_16x16x32_bf16 v[4:7], v[180:183], v[212:215], v[4:7]
	v_mfma_f32_16x16x32_bf16 v[4:7], v[184:187], v[216:219], v[4:7]
	s_setprio 0
	s_barrier
	s_add_i32 s54, 0, 0x18000
	v_add_u32_e32 v155, s54, v149
	s_add_i32 s55, 0, 0x1c000
	ds_read_b128 v[156:159], v155
	ds_read_b128 v[160:163], v155 offset:1024
	ds_read_b128 v[164:167], v155 offset:2048
	ds_read_b128 v[168:171], v155 offset:3072
	v_add_u32_e32 v155, s55, v149
	ds_read_b128 v[172:175], v155
	ds_read_b128 v[176:179], v155 offset:1024
	ds_read_b128 v[180:183], v155 offset:2048
	ds_read_b128 v[184:187], v155 offset:3072
	s_add_u32 s30, s30, 0x80000
	s_addc_u32 s31, s31, 0
	s_mov_b32 m0, s40
	v_lshl_add_u64 v[226:227], s[30:31], 0, v[136:137]
	ds_read_b128 v[188:191], v153 offset:32768
	ds_read_b128 v[192:195], v153 offset:33792
	ds_read_b128 v[196:199], v153 offset:34816
	ds_read_b128 v[200:203], v153 offset:35840
	ds_read_b128 v[204:207], v153 offset:36864
	ds_read_b128 v[208:211], v153 offset:37888
	ds_read_b128 v[212:215], v153 offset:38912
	ds_read_b128 v[216:219], v153 offset:39936
	global_load_lds_dwordx4 v[226:227], off
	v_lshl_add_u64 v[226:227], s[30:31], 0, v[132:133]
	s_mov_b32 m0, s41
	s_nop 0
	global_load_lds_dwordx4 v[226:227], off
	s_waitcnt vmcnt(8)
	s_waitcnt lgkmcnt(0)
	s_barrier
	s_setprio 1
	s_waitcnt lgkmcnt(0)
	v_mfma_f32_16x16x32_bf16 v[116:119], v[156:159], v[188:191], v[116:119]
	v_mfma_f32_16x16x32_bf16 v[116:119], v[160:163], v[192:195], v[116:119]
	v_mfma_f32_16x16x32_bf16 v[112:115], v[164:167], v[188:191], v[112:115]
	v_mfma_f32_16x16x32_bf16 v[112:115], v[168:171], v[192:195], v[112:115]
	v_mfma_f32_16x16x32_bf16 v[100:103], v[156:159], v[196:199], v[100:103]
	v_mfma_f32_16x16x32_bf16 v[100:103], v[160:163], v[200:203], v[100:103]
	v_mfma_f32_16x16x32_bf16 v[96:99], v[164:167], v[196:199], v[96:99]
	v_mfma_f32_16x16x32_bf16 v[96:99], v[168:171], v[200:203], v[96:99]
	v_mfma_f32_16x16x32_bf16 v[84:87], v[156:159], v[204:207], v[84:87]
	v_mfma_f32_16x16x32_bf16 v[84:87], v[160:163], v[208:211], v[84:87]
	v_mfma_f32_16x16x32_bf16 v[80:83], v[164:167], v[204:207], v[80:83]
	v_mfma_f32_16x16x32_bf16 v[80:83], v[168:171], v[208:211], v[80:83]
	v_mfma_f32_16x16x32_bf16 v[68:71], v[156:159], v[212:215], v[68:71]
	v_mfma_f32_16x16x32_bf16 v[68:71], v[160:163], v[216:219], v[68:71]
	v_mfma_f32_16x16x32_bf16 v[64:67], v[164:167], v[212:215], v[64:67]
	v_mfma_f32_16x16x32_bf16 v[64:67], v[168:171], v[216:219], v[64:67]
	s_setprio 0
	s_setprio 1
	v_mfma_f32_16x16x32_bf16 v[124:127], v[172:175], v[188:191], v[124:127]
	v_mfma_f32_16x16x32_bf16 v[124:127], v[176:179], v[192:195], v[124:127]
	v_mfma_f32_16x16x32_bf16 v[120:123], v[180:183], v[188:191], v[120:123]
	v_mfma_f32_16x16x32_bf16 v[120:123], v[184:187], v[192:195], v[120:123]
	v_mfma_f32_16x16x32_bf16 v[108:111], v[172:175], v[196:199], v[108:111]
	v_mfma_f32_16x16x32_bf16 v[108:111], v[176:179], v[200:203], v[108:111]
	v_mfma_f32_16x16x32_bf16 v[104:107], v[180:183], v[196:199], v[104:107]
	v_mfma_f32_16x16x32_bf16 v[104:107], v[184:187], v[200:203], v[104:107]
	v_mfma_f32_16x16x32_bf16 v[92:95], v[172:175], v[204:207], v[92:95]
	v_mfma_f32_16x16x32_bf16 v[92:95], v[176:179], v[208:211], v[92:95]
	v_mfma_f32_16x16x32_bf16 v[88:91], v[180:183], v[204:207], v[88:91]
	v_mfma_f32_16x16x32_bf16 v[88:91], v[184:187], v[208:211], v[88:91]
	v_mfma_f32_16x16x32_bf16 v[76:79], v[172:175], v[212:215], v[76:79]
	v_mfma_f32_16x16x32_bf16 v[76:79], v[176:179], v[216:219], v[76:79]
	v_mfma_f32_16x16x32_bf16 v[72:75], v[180:183], v[212:215], v[72:75]
	v_mfma_f32_16x16x32_bf16 v[72:75], v[184:187], v[216:219], v[72:75]
	s_setprio 0
	s_barrier
	s_add_i32 s30, s54, s36
	v_lshl_add_u64 v[146:147], v[146:147], 0, s[12:13]
	s_mov_b32 m0, s30
	ds_read_b128 v[188:191], v153 offset:49152
	ds_read_b128 v[192:195], v153 offset:50176
	ds_read_b128 v[196:199], v153 offset:51200
	ds_read_b128 v[200:203], v153 offset:52224
	ds_read_b128 v[204:207], v153 offset:53248
	ds_read_b128 v[208:211], v153 offset:54272
	ds_read_b128 v[212:215], v153 offset:55296
	ds_read_b128 v[216:219], v153 offset:56320
	global_load_lds_dwordx4 v[146:147], off
	s_add_i32 m0, s30, 0x2000
	s_add_u32 s28, s28, 0x80080
	v_lshl_add_u64 v[146:147], v[220:221], 0, s[12:13]
	s_addc_u32 s29, s29, 0
	s_add_i32 s30, s55, s36
	global_load_lds_dwordx4 v[146:147], off
	v_lshl_add_u64 v[146:147], s[28:29], 0, v[134:135]
	s_mov_b32 m0, s30
	s_nop 0
	global_load_lds_dwordx4 v[146:147], off
	v_lshl_add_u64 v[146:147], s[28:29], 0, v[130:131]
	s_add_i32 m0, s30, 0x2000
	s_nop 0
	global_load_lds_dwordx4 v[146:147], off
	v_lshl_add_u64 v[146:147], v[222:223], 0, s[12:13]
	s_mov_b32 m0, s43
	s_nop 0
	global_load_lds_dwordx4 v[146:147], off
	v_lshl_add_u64 v[146:147], v[224:225], 0, s[12:13]
	s_mov_b32 m0, s44
	s_nop 0
	global_load_lds_dwordx4 v[146:147], off
	s_waitcnt vmcnt(8)
	s_waitcnt lgkmcnt(0)
	s_barrier
	s_setprio 1
	s_waitcnt lgkmcnt(0)
	v_mfma_f32_16x16x32_bf16 v[52:55], v[156:159], v[188:191], v[52:55]
	v_mfma_f32_16x16x32_bf16 v[52:55], v[160:163], v[192:195], v[52:55]
	v_mfma_f32_16x16x32_bf16 v[48:51], v[164:167], v[188:191], v[48:51]
	v_mfma_f32_16x16x32_bf16 v[48:51], v[168:171], v[192:195], v[48:51]
	v_mfma_f32_16x16x32_bf16 v[36:39], v[156:159], v[196:199], v[36:39]
	v_mfma_f32_16x16x32_bf16 v[36:39], v[160:163], v[200:203], v[36:39]
	v_mfma_f32_16x16x32_bf16 v[32:35], v[164:167], v[196:199], v[32:35]
	v_mfma_f32_16x16x32_bf16 v[32:35], v[168:171], v[200:203], v[32:35]
	v_mfma_f32_16x16x32_bf16 v[20:23], v[156:159], v[204:207], v[20:23]
	v_mfma_f32_16x16x32_bf16 v[20:23], v[160:163], v[208:211], v[20:23]
	v_mfma_f32_16x16x32_bf16 v[16:19], v[164:167], v[204:207], v[16:19]
	v_mfma_f32_16x16x32_bf16 v[16:19], v[168:171], v[208:211], v[16:19]
	v_mfma_f32_16x16x32_bf16 v[8:11], v[156:159], v[212:215], v[8:11]
	v_mfma_f32_16x16x32_bf16 v[8:11], v[160:163], v[216:219], v[8:11]
	v_mfma_f32_16x16x32_bf16 v[0:3], v[164:167], v[212:215], v[0:3]
	v_mfma_f32_16x16x32_bf16 v[0:3], v[168:171], v[216:219], v[0:3]
	s_setprio 0
	s_setprio 1
	v_mfma_f32_16x16x32_bf16 v[60:63], v[172:175], v[188:191], v[60:63]
	v_mfma_f32_16x16x32_bf16 v[60:63], v[176:179], v[192:195], v[60:63]
	v_mfma_f32_16x16x32_bf16 v[56:59], v[180:183], v[188:191], v[56:59]
	v_mfma_f32_16x16x32_bf16 v[56:59], v[184:187], v[192:195], v[56:59]
	v_mfma_f32_16x16x32_bf16 v[44:47], v[172:175], v[196:199], v[44:47]
	v_mfma_f32_16x16x32_bf16 v[44:47], v[176:179], v[200:203], v[44:47]
	v_mfma_f32_16x16x32_bf16 v[40:43], v[180:183], v[196:199], v[40:43]
	v_mfma_f32_16x16x32_bf16 v[40:43], v[184:187], v[200:203], v[40:43]
	v_mfma_f32_16x16x32_bf16 v[28:31], v[172:175], v[204:207], v[28:31]
	v_mfma_f32_16x16x32_bf16 v[28:31], v[176:179], v[208:211], v[28:31]
	v_mfma_f32_16x16x32_bf16 v[24:27], v[180:183], v[204:207], v[24:27]
	v_mfma_f32_16x16x32_bf16 v[24:27], v[184:187], v[208:211], v[24:27]
	v_mfma_f32_16x16x32_bf16 v[12:15], v[172:175], v[212:215], v[12:15]
	v_mfma_f32_16x16x32_bf16 v[12:15], v[176:179], v[216:219], v[12:15]
	v_mfma_f32_16x16x32_bf16 v[4:7], v[180:183], v[212:215], v[4:7]
	v_mfma_f32_16x16x32_bf16 v[4:7], v[184:187], v[216:219], v[4:7]
	s_setprio 0
	s_barrier
	s_add_i32 s53, s53, 2
	s_add_u32 s26, s26, 0x100
	s_addc_u32 s27, s27, 0
	s_add_u32 s51, s51, 0x100
	s_addc_u32 s52, s52, 0
	s_cmp_gt_u32 s53, 29
	s_cbranch_scc0 .LBB0_671
	s_and_b64 vcc, exec, s[14:15]
	s_cbranch_vccz .LBB0_674
	s_barrier

.LBB0_849:
	v_add_u32_e32 v164, s40, v129
	v_add_u32_e32 v173, s41, v129
	s_add_u32 s22, s14, s20
	ds_read_b128 v[152:155], v164
	ds_read_b128 v[156:159], v164 offset:1024
	ds_read_b128 v[160:163], v164 offset:2048
	ds_read_b128 v[164:167], v164 offset:3072
	ds_read_b128 v[168:171], v173
	ds_read_b128 v[174:177], v173 offset:1024
	ds_read_b128 v[178:181], v173 offset:2048
	ds_read_b128 v[182:185], v173 offset:3072
	s_addc_u32 s23, s15, s21
	s_add_u32 s22, s22, 0x100
	s_addc_u32 s23, s23, 0
	s_add_u32 s48, s45, s20
	s_addc_u32 s49, s46, s21
	s_cmpk_eq_i32 s20, 0x2b00
	s_cselect_b32 s25, s19, s23
	s_cselect_b32 s24, s18, s22
	s_cselect_b32 s23, s7, s49
	s_cselect_b32 s22, s6, s48
	v_lshl_add_u64 v[218:219], v[146:147], 0, s[20:21]
	s_add_i32 m0, s33, 0xc000
	ds_read_b128 v[186:189], v151
	ds_read_b128 v[190:193], v151 offset:1024
	ds_read_b128 v[194:197], v151 offset:2048
	ds_read_b128 v[198:201], v151 offset:3072
	ds_read_b128 v[202:205], v151 offset:4096
	ds_read_b128 v[206:209], v151 offset:5120
	ds_read_b128 v[210:213], v151 offset:6144
	ds_read_b128 v[214:217], v151 offset:7168
	global_load_lds_dwordx4 v[218:219], off
	v_lshl_add_u64 v[218:219], v[148:149], 0, s[20:21]
	s_add_i32 m0, s33, 0xe000
	s_nop 0
	global_load_lds_dwordx4 v[218:219], off
	s_waitcnt vmcnt(8)
	s_waitcnt lgkmcnt(0)
	s_barrier
	s_setprio 1
	s_waitcnt lgkmcnt(0)
	v_mfma_f32_16x16x32_bf16 v[124:127], v[152:155], v[186:189], v[124:127]
	v_mfma_f32_16x16x32_bf16 v[124:127], v[156:159], v[190:193], v[124:127]
	v_mfma_f32_16x16x32_bf16 v[120:123], v[160:163], v[186:189], v[120:123]
	v_mfma_f32_16x16x32_bf16 v[120:123], v[164:167], v[190:193], v[120:123]
	v_mfma_f32_16x16x32_bf16 v[108:111], v[152:155], v[194:197], v[108:111]
	v_mfma_f32_16x16x32_bf16 v[108:111], v[156:159], v[198:201], v[108:111]
	v_mfma_f32_16x16x32_bf16 v[104:107], v[160:163], v[194:197], v[104:107]
	v_mfma_f32_16x16x32_bf16 v[104:107], v[164:167], v[198:201], v[104:107]
	v_mfma_f32_16x16x32_bf16 v[92:95], v[152:155], v[202:205], v[92:95]
	v_mfma_f32_16x16x32_bf16 v[92:95], v[156:159], v[206:209], v[92:95]
	v_mfma_f32_16x16x32_bf16 v[88:91], v[160:163], v[202:205], v[88:91]
	v_mfma_f32_16x16x32_bf16 v[88:91], v[164:167], v[206:209], v[88:91]
	v_mfma_f32_16x16x32_bf16 v[76:79], v[152:155], v[210:213], v[76:79]
	v_mfma_f32_16x16x32_bf16 v[76:79], v[156:159], v[214:217], v[76:79]
	v_mfma_f32_16x16x32_bf16 v[72:75], v[160:163], v[210:213], v[72:75]
	v_mfma_f32_16x16x32_bf16 v[72:75], v[164:167], v[214:217], v[72:75]
	s_setprio 0
	s_setprio 1
	v_mfma_f32_16x16x32_bf16 v[116:119], v[168:171], v[186:189], v[116:119]
	v_mfma_f32_16x16x32_bf16 v[116:119], v[174:177], v[190:193], v[116:119]
	v_mfma_f32_16x16x32_bf16 v[112:115], v[178:181], v[186:189], v[112:115]
	v_mfma_f32_16x16x32_bf16 v[112:115], v[182:185], v[190:193], v[112:115]
	v_mfma_f32_16x16x32_bf16 v[100:103], v[168:171], v[194:197], v[100:103]
	v_mfma_f32_16x16x32_bf16 v[100:103], v[174:177], v[198:201], v[100:103]
	v_mfma_f32_16x16x32_bf16 v[96:99], v[178:181], v[194:197], v[96:99]
	v_mfma_f32_16x16x32_bf16 v[96:99], v[182:185], v[198:201], v[96:99]
	v_mfma_f32_16x16x32_bf16 v[84:87], v[168:171], v[202:205], v[84:87]
	v_mfma_f32_16x16x32_bf16 v[84:87], v[174:177], v[206:209], v[84:87]
	v_mfma_f32_16x16x32_bf16 v[80:83], v[178:181], v[202:205], v[80:83]
	v_mfma_f32_16x16x32_bf16 v[80:83], v[182:185], v[206:209], v[80:83]
	v_mfma_f32_16x16x32_bf16 v[68:71], v[168:171], v[210:213], v[68:71]
	v_mfma_f32_16x16x32_bf16 v[68:71], v[174:177], v[214:217], v[68:71]
	v_mfma_f32_16x16x32_bf16 v[64:67], v[178:181], v[210:213], v[64:67]
	v_mfma_f32_16x16x32_bf16 v[64:67], v[182:185], v[214:217], v[64:67]
	s_setprio 0
	s_barrier
	s_add_i32 s48, s40, s31
	v_lshl_add_u64 v[218:219], s[22:23], 0, v[132:133]
	s_mov_b32 m0, s48
	ds_read_b128 v[186:189], v151 offset:16384
	ds_read_b128 v[190:193], v151 offset:17408
	ds_read_b128 v[194:197], v151 offset:18432
	ds_read_b128 v[198:201], v151 offset:19456
	ds_read_b128 v[202:205], v151 offset:20480
	ds_read_b128 v[206:209], v151 offset:21504
	ds_read_b128 v[210:213], v151 offset:22528
	ds_read_b128 v[214:217], v151 offset:23552
	global_load_lds_dwordx4 v[218:219], off
	s_add_i32 m0, s48, 0x2000
	s_add_u32 s48, s22, 0x160000
	v_lshl_add_u64 v[220:221], s[22:23], 0, v[136:137]
	s_addc_u32 s49, s23, 0
	s_add_i32 s50, s41, s31
	global_load_lds_dwordx4 v[220:221], off
	v_lshl_add_u64 v[222:223], s[48:49], 0, v[132:133]
	s_mov_b32 m0, s50
	v_lshl_add_u64 v[224:225], s[24:25], 0, v[134:135]
	global_load_lds_dwordx4 v[222:223], off
	v_lshl_add_u64 v[222:223], s[48:49], 0, v[136:137]
	s_add_i32 m0, s50, 0x2000
	s_nop 0
	global_load_lds_dwordx4 v[222:223], off
	v_lshl_add_u64 v[222:223], s[24:25], 0, v[130:131]
	s_mov_b32 m0, s33
	s_nop 0
	global_load_lds_dwordx4 v[222:223], off
	s_mov_b32 m0, s34
	s_nop 0
	global_load_lds_dwordx4 v[224:225], off
	s_waitcnt vmcnt(8)
	s_waitcnt lgkmcnt(0)
	s_barrier
	s_setprio 1
	s_waitcnt lgkmcnt(0)
	v_mfma_f32_16x16x32_bf16 v[60:63], v[152:155], v[186:189], v[60:63]
	v_mfma_f32_16x16x32_bf16 v[60:63], v[156:159], v[190:193], v[60:63]
	v_mfma_f32_16x16x32_bf16 v[56:59], v[160:163], v[186:189], v[56:59]
	v_mfma_f32_16x16x32_bf16 v[56:59], v[164:167], v[190:193], v[56:59]
	v_mfma_f32_16x16x32_bf16 v[44:47], v[152:155], v[194:197], v[44:47]
	v_mfma_f32_16x16x32_bf16 v[44:47], v[156:159], v[198:201], v[44:47]
	v_mfma_f32_16x16x32_bf16 v[40:43], v[160:163], v[194:197], v[40:43]
	v_mfma_f32_16x16x32_bf16 v[40:43], v[164:167], v[198:201], v[40:43]
	v_mfma_f32_16x16x32_bf16 v[28:31], v[152:155], v[202:205], v[28:31]
	v_mfma_f32_16x16x32_bf16 v[28:31], v[156:159], v[206:209], v[28:31]
	v_mfma_f32_16x16x32_bf16 v[24:27], v[160:163], v[202:205], v[24:27]
	v_mfma_f32_16x16x32_bf16 v[24:27], v[164:167], v[206:209], v[24:27]
	v_mfma_f32_16x16x32_bf16 v[12:15], v[152:155], v[210:213], v[12:15]
	v_mfma_f32_16x16x32_bf16 v[12:15], v[156:159], v[214:217], v[12:15]
	v_mfma_f32_16x16x32_bf16 v[8:11], v[160:163], v[210:213], v[8:11]
	v_mfma_f32_16x16x32_bf16 v[8:11], v[164:167], v[214:217], v[8:11]
	s_setprio 0
	s_setprio 1
	v_mfma_f32_16x16x32_bf16 v[52:55], v[168:171], v[186:189], v[52:55]
	v_mfma_f32_16x16x32_bf16 v[52:55], v[174:177], v[190:193], v[52:55]
	v_mfma_f32_16x16x32_bf16 v[48:51], v[178:181], v[186:189], v[48:51]
	v_mfma_f32_16x16x32_bf16 v[48:51], v[182:185], v[190:193], v[48:51]
	v_mfma_f32_16x16x32_bf16 v[36:39], v[168:171], v[194:197], v[36:39]
	v_mfma_f32_16x16x32_bf16 v[36:39], v[174:177], v[198:201], v[36:39]
	v_mfma_f32_16x16x32_bf16 v[32:35], v[178:181], v[194:197], v[32:35]
	v_mfma_f32_16x16x32_bf16 v[32:35], v[182:185], v[198:201], v[32:35]
	v_mfma_f32_16x16x32_bf16 v[20:23], v[168:171], v[202:205], v[20:23]
	v_mfma_f32_16x16x32_bf16 v[20:23], v[174:177], v[206:209], v[20:23]
	v_mfma_f32_16x16x32_bf16 v[16:19], v[178:181], v[202:205], v[16:19]
	v_mfma_f32_16x16x32_bf16 v[16:19], v[182:185], v[206:209], v[16:19]
	v_mfma_f32_16x16x32_bf16 v[4:7], v[168:171], v[210:213], v[4:7]
	v_mfma_f32_16x16x32_bf16 v[4:7], v[174:177], v[214:217], v[4:7]
	v_mfma_f32_16x16x32_bf16 v[0:3], v[178:181], v[210:213], v[0:3]
	v_mfma_f32_16x16x32_bf16 v[0:3], v[182:185], v[214:217], v[0:3]
	s_setprio 0
	s_barrier
	s_add_i32 s48, 0, 0x18000
	s_add_i32 s49, 0, 0x1c000
	v_add_u32_e32 v164, s48, v129
	v_add_u32_e32 v173, s49, v129
	ds_read_b128 v[152:155], v164
	ds_read_b128 v[156:159], v164 offset:1024
	ds_read_b128 v[160:163], v164 offset:2048
	ds_read_b128 v[164:167], v164 offset:3072
	ds_read_b128 v[168:171], v173
	ds_read_b128 v[174:177], v173 offset:1024
	ds_read_b128 v[178:181], v173 offset:2048
	ds_read_b128 v[182:185], v173 offset:3072
	s_add_u32 s24, s24, 0x160000
	s_addc_u32 s25, s25, 0
	s_mov_b32 m0, s35
	v_lshl_add_u64 v[226:227], s[24:25], 0, v[130:131]
	ds_read_b128 v[186:189], v151 offset:32768
	ds_read_b128 v[190:193], v151 offset:33792
	ds_read_b128 v[194:197], v151 offset:34816
	ds_read_b128 v[198:201], v151 offset:35840
	ds_read_b128 v[202:205], v151 offset:36864
	ds_read_b128 v[206:209], v151 offset:37888
	ds_read_b128 v[210:213], v151 offset:38912
	ds_read_b128 v[214:217], v151 offset:39936
	global_load_lds_dwordx4 v[226:227], off
	v_lshl_add_u64 v[226:227], s[24:25], 0, v[134:135]
	s_mov_b32 m0, s36
	s_nop 0
	global_load_lds_dwordx4 v[226:227], off
	s_waitcnt vmcnt(8)
	s_waitcnt lgkmcnt(0)
	s_barrier
	s_setprio 1
	s_waitcnt lgkmcnt(0)
	v_mfma_f32_16x16x32_bf16 v[124:127], v[152:155], v[186:189], v[124:127]
	v_mfma_f32_16x16x32_bf16 v[124:127], v[156:159], v[190:193], v[124:127]
	v_mfma_f32_16x16x32_bf16 v[120:123], v[160:163], v[186:189], v[120:123]
	v_mfma_f32_16x16x32_bf16 v[120:123], v[164:167], v[190:193], v[120:123]
	v_mfma_f32_16x16x32_bf16 v[108:111], v[152:155], v[194:197], v[108:111]
	v_mfma_f32_16x16x32_bf16 v[108:111], v[156:159], v[198:201], v[108:111]
	v_mfma_f32_16x16x32_bf16 v[104:107], v[160:163], v[194:197], v[104:107]
	v_mfma_f32_16x16x32_bf16 v[104:107], v[164:167], v[198:201], v[104:107]
	v_mfma_f32_16x16x32_bf16 v[92:95], v[152:155], v[202:205], v[92:95]
	v_mfma_f32_16x16x32_bf16 v[92:95], v[156:159], v[206:209], v[92:95]
	v_mfma_f32_16x16x32_bf16 v[88:91], v[160:163], v[202:205], v[88:91]
	v_mfma_f32_16x16x32_bf16 v[88:91], v[164:167], v[206:209], v[88:91]
	v_mfma_f32_16x16x32_bf16 v[76:79], v[152:155], v[210:213], v[76:79]
	v_mfma_f32_16x16x32_bf16 v[76:79], v[156:159], v[214:217], v[76:79]
	v_mfma_f32_16x16x32_bf16 v[72:75], v[160:163], v[210:213], v[72:75]
	v_mfma_f32_16x16x32_bf16 v[72:75], v[164:167], v[214:217], v[72:75]
	s_setprio 0
	s_setprio 1
	v_mfma_f32_16x16x32_bf16 v[116:119], v[168:171], v[186:189], v[116:119]
	v_mfma_f32_16x16x32_bf16 v[116:119], v[174:177], v[190:193], v[116:119]
	v_mfma_f32_16x16x32_bf16 v[112:115], v[178:181], v[186:189], v[112:115]
	v_mfma_f32_16x16x32_bf16 v[112:115], v[182:185], v[190:193], v[112:115]
	v_mfma_f32_16x16x32_bf16 v[100:103], v[168:171], v[194:197], v[100:103]
	v_mfma_f32_16x16x32_bf16 v[100:103], v[174:177], v[198:201], v[100:103]
	v_mfma_f32_16x16x32_bf16 v[96:99], v[178:181], v[194:197], v[96:99]
	v_mfma_f32_16x16x32_bf16 v[96:99], v[182:185], v[198:201], v[96:99]
	v_mfma_f32_16x16x32_bf16 v[84:87], v[168:171], v[202:205], v[84:87]
	v_mfma_f32_16x16x32_bf16 v[84:87], v[174:177], v[206:209], v[84:87]
	v_mfma_f32_16x16x32_bf16 v[80:83], v[178:181], v[202:205], v[80:83]
	v_mfma_f32_16x16x32_bf16 v[80:83], v[182:185], v[206:209], v[80:83]
	v_mfma_f32_16x16x32_bf16 v[68:71], v[168:171], v[210:213], v[68:71]
	v_mfma_f32_16x16x32_bf16 v[68:71], v[174:177], v[214:217], v[68:71]
	v_mfma_f32_16x16x32_bf16 v[64:67], v[178:181], v[210:213], v[64:67]
	v_mfma_f32_16x16x32_bf16 v[64:67], v[182:185], v[214:217], v[64:67]
	s_setprio 0
	s_barrier
	s_add_i32 s24, s48, s31
	v_lshl_add_u64 v[218:219], v[218:219], 0, s[16:17]
	s_mov_b32 m0, s24
	ds_read_b128 v[186:189], v151 offset:49152
	ds_read_b128 v[190:193], v151 offset:50176
	ds_read_b128 v[194:197], v151 offset:51200
	ds_read_b128 v[198:201], v151 offset:52224
	ds_read_b128 v[202:205], v151 offset:53248
	ds_read_b128 v[206:209], v151 offset:54272
	ds_read_b128 v[210:213], v151 offset:55296
	ds_read_b128 v[214:217], v151 offset:56320
	global_load_lds_dwordx4 v[218:219], off
	s_add_i32 m0, s24, 0x2000
	s_add_u32 s22, s22, 0x160080
	v_lshl_add_u64 v[218:219], v[220:221], 0, s[16:17]
	s_addc_u32 s23, s23, 0
	s_add_i32 s24, s49, s31
	global_load_lds_dwordx4 v[218:219], off
	v_lshl_add_u64 v[218:219], s[22:23], 0, v[132:133]
	s_mov_b32 m0, s24
	s_nop 0
	global_load_lds_dwordx4 v[218:219], off
	v_lshl_add_u64 v[218:219], s[22:23], 0, v[136:137]
	s_add_i32 m0, s24, 0x2000
	s_nop 0
	global_load_lds_dwordx4 v[218:219], off
	v_lshl_add_u64 v[218:219], v[222:223], 0, s[16:17]
	s_mov_b32 m0, s37
	s_nop 0
	global_load_lds_dwordx4 v[218:219], off
	v_lshl_add_u64 v[218:219], v[224:225], 0, s[16:17]
	s_mov_b32 m0, s38
	s_nop 0
	global_load_lds_dwordx4 v[218:219], off
	s_waitcnt vmcnt(8)
	s_waitcnt lgkmcnt(0)
	s_barrier
	s_setprio 1
	s_waitcnt lgkmcnt(0)
	v_mfma_f32_16x16x32_bf16 v[60:63], v[152:155], v[186:189], v[60:63]
	v_mfma_f32_16x16x32_bf16 v[60:63], v[156:159], v[190:193], v[60:63]
	v_mfma_f32_16x16x32_bf16 v[56:59], v[160:163], v[186:189], v[56:59]
	v_mfma_f32_16x16x32_bf16 v[56:59], v[164:167], v[190:193], v[56:59]
	v_mfma_f32_16x16x32_bf16 v[44:47], v[152:155], v[194:197], v[44:47]
	v_mfma_f32_16x16x32_bf16 v[44:47], v[156:159], v[198:201], v[44:47]
	v_mfma_f32_16x16x32_bf16 v[40:43], v[160:163], v[194:197], v[40:43]
	v_mfma_f32_16x16x32_bf16 v[40:43], v[164:167], v[198:201], v[40:43]
	v_mfma_f32_16x16x32_bf16 v[28:31], v[152:155], v[202:205], v[28:31]
	v_mfma_f32_16x16x32_bf16 v[28:31], v[156:159], v[206:209], v[28:31]
	v_mfma_f32_16x16x32_bf16 v[24:27], v[160:163], v[202:205], v[24:27]
	v_mfma_f32_16x16x32_bf16 v[24:27], v[164:167], v[206:209], v[24:27]
	v_mfma_f32_16x16x32_bf16 v[12:15], v[152:155], v[210:213], v[12:15]
	v_mfma_f32_16x16x32_bf16 v[12:15], v[156:159], v[214:217], v[12:15]
	v_mfma_f32_16x16x32_bf16 v[8:11], v[160:163], v[210:213], v[8:11]
	v_mfma_f32_16x16x32_bf16 v[8:11], v[164:167], v[214:217], v[8:11]
	s_setprio 0
	s_setprio 1
	v_mfma_f32_16x16x32_bf16 v[52:55], v[168:171], v[186:189], v[52:55]
	v_mfma_f32_16x16x32_bf16 v[52:55], v[174:177], v[190:193], v[52:55]
	v_mfma_f32_16x16x32_bf16 v[48:51], v[178:181], v[186:189], v[48:51]
	v_mfma_f32_16x16x32_bf16 v[48:51], v[182:185], v[190:193], v[48:51]
	v_mfma_f32_16x16x32_bf16 v[36:39], v[168:171], v[194:197], v[36:39]
	v_mfma_f32_16x16x32_bf16 v[36:39], v[174:177], v[198:201], v[36:39]
	v_mfma_f32_16x16x32_bf16 v[32:35], v[178:181], v[194:197], v[32:35]
	v_mfma_f32_16x16x32_bf16 v[32:35], v[182:185], v[198:201], v[32:35]
	v_mfma_f32_16x16x32_bf16 v[20:23], v[168:171], v[202:205], v[20:23]
	v_mfma_f32_16x16x32_bf16 v[20:23], v[174:177], v[206:209], v[20:23]
	v_mfma_f32_16x16x32_bf16 v[16:19], v[178:181], v[202:205], v[16:19]
	v_mfma_f32_16x16x32_bf16 v[16:19], v[182:185], v[206:209], v[16:19]
	v_mfma_f32_16x16x32_bf16 v[4:7], v[168:171], v[210:213], v[4:7]
	v_mfma_f32_16x16x32_bf16 v[4:7], v[174:177], v[214:217], v[4:7]
	v_mfma_f32_16x16x32_bf16 v[0:3], v[178:181], v[210:213], v[0:3]
	v_mfma_f32_16x16x32_bf16 v[0:3], v[182:185], v[214:217], v[0:3]
	s_setprio 0
	s_barrier
	s_add_i32 s47, s47, 2
	s_add_u32 s20, s20, 0x100
	s_addc_u32 s21, s21, 0
	s_cmpk_gt_u32 s47, 0x55
	s_cbranch_scc0 .LBB0_849
	s_add_u32 s20, s45, 0xffffff00
	s_addc_u32 s21, s46, -1
	s_and_b64 vcc, exec, s[4:5]
	s_cbranch_vccnz .LBB0_852
	v_mov_b32_e32 v0, 0
	s_mov_b32 s12, s42
	s_mov_b32 s13, s43
	s_mov_b64 s[14:15], s[18:19]
	s_mov_b32 s39, s44
	v_mov_b32_e32 v1, v0
	v_mov_b32_e32 v2, v0
	v_mov_b32_e32 v3, v0
	v_mov_b32_e32 v4, v0
	v_mov_b32_e32 v5, v0
	v_mov_b32_e32 v6, v0
	v_mov_b32_e32 v7, v0
	v_mov_b32_e32 v16, v0
	v_mov_b32_e32 v17, v0
	v_mov_b32_e32 v18, v0
	v_mov_b32_e32 v19, v0
	v_mov_b32_e32 v20, v0
	v_mov_b32_e32 v21, v0
	v_mov_b32_e32 v22, v0
	v_mov_b32_e32 v23, v0
	v_mov_b32_e32 v32, v0
	v_mov_b32_e32 v33, v0
	v_mov_b32_e32 v34, v0
	v_mov_b32_e32 v35, v0
	v_mov_b32_e32 v36, v0
	v_mov_b32_e32 v37, v0
	v_mov_b32_e32 v38, v0
	v_mov_b32_e32 v39, v0
	v_mov_b32_e32 v48, v0
	v_mov_b32_e32 v49, v0
	v_mov_b32_e32 v50, v0
	v_mov_b32_e32 v51, v0
	v_mov_b32_e32 v52, v0
	v_mov_b32_e32 v53, v0
	v_mov_b32_e32 v54, v0
	v_mov_b32_e32 v55, v0
	v_mov_b32_e32 v8, v0
	v_mov_b32_e32 v9, v0
	v_mov_b32_e32 v10, v0
	v_mov_b32_e32 v11, v0
	v_mov_b32_e32 v12, v0
	v_mov_b32_e32 v13, v0
	v_mov_b32_e32 v14, v0
	v_mov_b32_e32 v15, v0
	v_mov_b32_e32 v24, v0
	v_mov_b32_e32 v25, v0
	v_mov_b32_e32 v26, v0
	v_mov_b32_e32 v27, v0
	v_mov_b32_e32 v28, v0
	v_mov_b32_e32 v29, v0
	v_mov_b32_e32 v30, v0
	v_mov_b32_e32 v31, v0
	v_mov_b32_e32 v40, v0
	v_mov_b32_e32 v41, v0
	v_mov_b32_e32 v42, v0
	v_mov_b32_e32 v43, v0
	v_mov_b32_e32 v44, v0
	v_mov_b32_e32 v45, v0
	v_mov_b32_e32 v46, v0
	v_mov_b32_e32 v47, v0
	v_mov_b32_e32 v56, v0
	v_mov_b32_e32 v57, v0
	v_mov_b32_e32 v58, v0
	v_mov_b32_e32 v59, v0
	v_mov_b32_e32 v60, v0
	v_mov_b32_e32 v61, v0
	v_mov_b32_e32 v62, v0
	v_mov_b32_e32 v63, v0
	v_mov_b32_e32 v64, v0
	v_mov_b32_e32 v65, v0
	v_mov_b32_e32 v66, v0
	v_mov_b32_e32 v67, v0
	v_mov_b32_e32 v68, v0
	v_mov_b32_e32 v69, v0
	v_mov_b32_e32 v70, v0
	v_mov_b32_e32 v71, v0
	v_mov_b32_e32 v80, v0
	v_mov_b32_e32 v81, v0
	v_mov_b32_e32 v82, v0
	v_mov_b32_e32 v83, v0
	v_mov_b32_e32 v84, v0
	v_mov_b32_e32 v85, v0
	v_mov_b32_e32 v86, v0
	v_mov_b32_e32 v87, v0
	v_mov_b32_e32 v96, v0
	v_mov_b32_e32 v97, v0
	v_mov_b32_e32 v98, v0
	v_mov_b32_e32 v99, v0
	v_mov_b32_e32 v100, v0
	v_mov_b32_e32 v101, v0
	v_mov_b32_e32 v102, v0
	v_mov_b32_e32 v103, v0
	v_mov_b32_e32 v112, v0
	v_mov_b32_e32 v113, v0
	v_mov_b32_e32 v114, v0
	v_mov_b32_e32 v115, v0
	v_mov_b32_e32 v116, v0
	v_mov_b32_e32 v117, v0
	v_mov_b32_e32 v118, v0
	v_mov_b32_e32 v119, v0
	v_mov_b32_e32 v72, v0
	v_mov_b32_e32 v73, v0
	v_mov_b32_e32 v74, v0
	v_mov_b32_e32 v75, v0
	v_mov_b32_e32 v76, v0
	v_mov_b32_e32 v77, v0
	v_mov_b32_e32 v78, v0
	v_mov_b32_e32 v79, v0
	v_mov_b32_e32 v88, v0
	v_mov_b32_e32 v89, v0
	v_mov_b32_e32 v90, v0
	v_mov_b32_e32 v91, v0
	v_mov_b32_e32 v92, v0
	v_mov_b32_e32 v93, v0
	v_mov_b32_e32 v94, v0
	v_mov_b32_e32 v95, v0
	v_mov_b32_e32 v104, v0
	v_mov_b32_e32 v105, v0
	v_mov_b32_e32 v106, v0
	v_mov_b32_e32 v107, v0
	v_mov_b32_e32 v108, v0
	v_mov_b32_e32 v109, v0
	v_mov_b32_e32 v110, v0
	v_mov_b32_e32 v111, v0
	v_mov_b32_e32 v120, v0
	v_mov_b32_e32 v121, v0
	v_mov_b32_e32 v122, v0
	v_mov_b32_e32 v123, v0
	v_mov_b32_e32 v124, v0
	v_mov_b32_e32 v125, v0
	v_mov_b32_e32 v126, v0
	v_mov_b32_e32 v127, v0
	s_andn2_b64 vcc, exec, s[0:1]
	s_cbranch_vccnz .LBB0_853
	s_branch .LBB0_854
